# MLA: serial OR chain (as the best version) + tile loop unrolled by 2 (no per-tile LDS address adds) + adjacent query-tile pairs for the 4 workgroups sharing a head in an XCD
# speedup vs baseline: 1.0107x; 1.0026x over previous
; #define WLK(n) do { asm volatile("s_waitcnt lgkmcnt(" #n ")" ::: "memory"); SBAR(); } while (0)
; #define RDN(S, dd, off) do { const int a_ = rb + (((dd) * 32 + h16) ^ sw); KRD(S##0, a_, off); KRD(S##1, a_, 8192 + (off)); } while (0)
; #define RDR(S, ks) do { const int a_ = rr + (((((ks) * 2 + hi)) ^ (r32 & 7)) << 4); KRD(S##0, a_, 0); KRD(S##1, a_, 4096); } while (0)
; #define MM1(S, d) do { p0 = __builtin_amdgcn_mfma_f32_32x32x16_bf16(S##0, qr[d], p0, 0, 0, 0); p1 = __builtin_amdgcn_mfma_f32_32x32x16_bf16(S##1, qr[d], p1, 0, 0, 0); } while (0)
; __device__ __forceinline__ void partialSM_pre(f32x16& p0, f32x16& p1, float& m_reg, float& alpha) {
;     constexpr float THR2 = THR * 1.4426950408889634f;
;     float pmax = p0[0];
; #pragma unroll
;     for (int r = 1; r < 16; ++r) pmax = fmaxf(pmax, p0[r]);
; #pragma unroll
;     for (int r = 0; r < 16; ++r) pmax = fmaxf(pmax, p1[r]);
;     { auto rr = __builtin_amdgcn_permlane32_swap(__float_as_uint(pmax), __float_as_uint(pmax), false, false);
;       pmax = fmaxf(__uint_as_float(rr[0]), __uint_as_float(rr[1])); }
;     if (__builtin_expect(__all(pmax <= THR2), 1)) { alpha = 1.f; }
;     else { const float d = fmaxf(pmax, 0.f); m_reg += d; alpha = __builtin_amdgcn_exp2f(-d);
; #pragma unroll
;         for (int r = 0; r < 16; ++r) { p0[r] -= d; p1[r] -= d; } }
; #pragma unroll
;     for (int r = 0; r < 16; ++r) p0[r] = __builtin_amdgcn_exp2f(p0[r]);
; }
; __device__ __forceinline__ void qk_mla(f32x16& p0, f32x16& p1, int kaddr, int r32, int hi, const bf16x8* qr) {
;     const int rb = kaddr + r32 * 256, sw = (r32 & 7) << 4, h16 = hi * 16;
;     const int rr = kaddr + 16384 + r32 * 128;
;     ...
;     bf16x8 A0, A1, B0, B1;
;     RDN(A, 0, 0); RDN(B, 1, 0);
;     WLK(2); MM1(A, 0); RDN(A, 2, 0);
;     WLK(2); MM1(B, 1); RDN(B, 3, 0);
;     WLK(2); MM1(A, 2); RDN(A, 0, 128);
;     WLK(2); MM1(B, 3); RDN(B, 1, 128);
;     WLK(2); MM1(A, 4); RDN(A, 2, 128);
;     WLK(2); MM1(B, 5); RDN(B, 3, 128);
;     WLK(2); MM1(A, 6); RDR(A, 0);
;     WLK(2); MM1(B, 7); RDR(B, 1);
;     WLK(2); MM1(A, 8); RDR(A, 2);
;     WLK(2); MM1(B, 9); RDR(B, 3);
;     WLK(2); MM1(A, 10);
;     WLK(0); MM1(B, 11);
.Lm16_nomask0:
	v_exp_f32_e32 v114, v114
	v_exp_f32_e32 v115, v115
	v_exp_f32_e32 v116, v116
	v_exp_f32_e32 v117, v117
	v_exp_f32_e32 v118, v118
	v_exp_f32_e32 v119, v119
	v_exp_f32_e32 v120, v120
	v_exp_f32_e32 v121, v121
	v_exp_f32_e32 v122, v122
	v_exp_f32_e32 v123, v123
	v_exp_f32_e32 v124, v124
	v_exp_f32_e32 v125, v125
	v_exp_f32_e32 v126, v126
	v_exp_f32_e32 v127, v127
	v_exp_f32_e32 v128, v128
	v_exp_f32_e32 v129, v129
	v_exp_f32_e32 v130, v130
	v_exp_f32_e32 v131, v131
	v_exp_f32_e32 v132, v132
	v_exp_f32_e32 v133, v133
	v_exp_f32_e32 v134, v134
	v_exp_f32_e32 v135, v135
	v_exp_f32_e32 v136, v136
	v_exp_f32_e32 v137, v137
	v_exp_f32_e32 v138, v138
	v_exp_f32_e32 v139, v139
	v_exp_f32_e32 v140, v140
	v_exp_f32_e32 v141, v141
	v_exp_f32_e32 v142, v142
	v_exp_f32_e32 v143, v143
	v_exp_f32_e32 v144, v144
	v_exp_f32_e32 v145, v145
	v_cvt_pk_bf16_f32 v164, v114, v115
	v_cvt_pk_bf16_f32 v165, v116, v117
	v_cvt_pk_bf16_f32 v166, v122, v123
	v_cvt_pk_bf16_f32 v167, v124, v125
	v_cvt_pk_bf16_f32 v168, v130, v131
	v_cvt_pk_bf16_f32 v169, v132, v133
	v_cvt_pk_bf16_f32 v170, v138, v139
	v_cvt_pk_bf16_f32 v171, v140, v141
	v_cvt_pk_bf16_f32 v172, v118, v119
	v_cvt_pk_bf16_f32 v173, v120, v121
	v_cvt_pk_bf16_f32 v174, v126, v127
	v_cvt_pk_bf16_f32 v175, v128, v129
	v_cvt_pk_bf16_f32 v176, v134, v135
	v_cvt_pk_bf16_f32 v177, v136, v137
	v_cvt_pk_bf16_f32 v178, v142, v143
	v_cvt_pk_bf16_f32 v179, v144, v145
	v_or3_b32 v220, v164, v165, v166
	v_or3_b32 v220, v220, v167, v168
	v_or3_b32 v220, v220, v169, v170
	v_or3_b32 v220, v220, v171, v172
	v_or3_b32 v220, v220, v173, v174
	v_or3_b32 v220, v220, v175, v176
	v_or3_b32 v220, v220, v177, v178
	v_or_b32_e32 v220, v220, v179
	v_and_b32_e32 v220, 0x40004000, v220
	v_cmp_eq_u32_e32 vcc, 0, v220
	s_cmp_eq_u64 vcc, exec
	s_cbranch_scc1 .Lm16_pv0
	ds_read_b128 v[180:183], v224 offset:0
	ds_read_b128 v[184:187], v224 offset:2048
	ds_read_b128 v[188:191], v224 offset:4096
	ds_read_b128 v[192:195], v224 offset:6144
	s_waitcnt lgkmcnt(3)
	v_mfma_f32_16x16x32_bf16 v[114:117], v[180:183], v[66:69], v[208:211]
	v_mfma_f32_16x16x32_bf16 v[118:121], v[180:183], v[90:93], v[212:215]
	ds_read_b128 v[180:183], v225 offset:0
	s_waitcnt lgkmcnt(3)
	v_mfma_f32_16x16x32_bf16 v[122:125], v[184:187], v[66:69], v[208:211]
	v_mfma_f32_16x16x32_bf16 v[126:129], v[184:187], v[90:93], v[212:215]
	ds_read_b128 v[184:187], v225 offset:2048
	s_waitcnt lgkmcnt(3)
	v_mfma_f32_16x16x32_bf16 v[130:133], v[188:191], v[66:69], v[208:211]
	v_mfma_f32_16x16x32_bf16 v[134:137], v[188:191], v[90:93], v[212:215]
	ds_read_b128 v[188:191], v225 offset:4096
	s_waitcnt lgkmcnt(3)
	v_mfma_f32_16x16x32_bf16 v[138:141], v[192:195], v[66:69], v[208:211]
	v_mfma_f32_16x16x32_bf16 v[142:145], v[192:195], v[90:93], v[212:215]
	ds_read_b128 v[192:195], v225 offset:6144
	s_waitcnt lgkmcnt(3)
	v_mfma_f32_16x16x32_bf16 v[114:117], v[180:183], v[70:73], v[114:117]
	v_mfma_f32_16x16x32_bf16 v[118:121], v[180:183], v[94:97], v[118:121]
	ds_read_b128 v[180:183], v224 offset:8192
	s_waitcnt lgkmcnt(3)
	v_mfma_f32_16x16x32_bf16 v[122:125], v[184:187], v[70:73], v[122:125]
	v_mfma_f32_16x16x32_bf16 v[126:129], v[184:187], v[94:97], v[126:129]
	ds_read_b128 v[184:187], v224 offset:10240
	s_waitcnt lgkmcnt(3)
	v_mfma_f32_16x16x32_bf16 v[130:133], v[188:191], v[70:73], v[130:133]
	v_mfma_f32_16x16x32_bf16 v[134:137], v[188:191], v[94:97], v[134:137]
	ds_read_b128 v[188:191], v224 offset:12288
	s_waitcnt lgkmcnt(3)
	v_mfma_f32_16x16x32_bf16 v[138:141], v[192:195], v[70:73], v[138:141]
	v_mfma_f32_16x16x32_bf16 v[142:145], v[192:195], v[94:97], v[142:145]
	ds_read_b128 v[192:195], v224 offset:14336
	s_waitcnt lgkmcnt(3)
	v_mfma_f32_16x16x32_bf16 v[114:117], v[180:183], v[74:77], v[114:117]
	v_mfma_f32_16x16x32_bf16 v[118:121], v[180:183], v[98:101], v[118:121]
	ds_read_b128 v[180:183], v225 offset:8192
	s_waitcnt lgkmcnt(3)
	v_mfma_f32_16x16x32_bf16 v[122:125], v[184:187], v[74:77], v[122:125]
	v_mfma_f32_16x16x32_bf16 v[126:129], v[184:187], v[98:101], v[126:129]
	ds_read_b128 v[184:187], v225 offset:10240
	s_waitcnt lgkmcnt(3)
	v_mfma_f32_16x16x32_bf16 v[130:133], v[188:191], v[74:77], v[130:133]
	v_mfma_f32_16x16x32_bf16 v[134:137], v[188:191], v[98:101], v[134:137]
	ds_read_b128 v[188:191], v225 offset:12288
	s_waitcnt lgkmcnt(3)
	v_mfma_f32_16x16x32_bf16 v[138:141], v[192:195], v[74:77], v[138:141]
	v_mfma_f32_16x16x32_bf16 v[142:145], v[192:195], v[98:101], v[142:145]
	ds_read_b128 v[192:195], v225 offset:14336
	s_waitcnt lgkmcnt(3)
	v_mfma_f32_16x16x32_bf16 v[114:117], v[180:183], v[78:81], v[114:117]
	v_mfma_f32_16x16x32_bf16 v[118:121], v[180:183], v[102:105], v[118:121]
	ds_read_b128 v[180:183], v224 offset:16384
	s_waitcnt lgkmcnt(3)
	v_mfma_f32_16x16x32_bf16 v[122:125], v[184:187], v[78:81], v[122:125]
	v_mfma_f32_16x16x32_bf16 v[126:129], v[184:187], v[102:105], v[126:129]
	ds_read_b128 v[184:187], v224 offset:18432
	s_waitcnt lgkmcnt(3)
	v_mfma_f32_16x16x32_bf16 v[130:133], v[188:191], v[78:81], v[130:133]
	v_mfma_f32_16x16x32_bf16 v[134:137], v[188:191], v[102:105], v[134:137]
	ds_read_b128 v[188:191], v224 offset:20480
	s_waitcnt lgkmcnt(3)
	v_mfma_f32_16x16x32_bf16 v[138:141], v[192:195], v[78:81], v[138:141]
	v_mfma_f32_16x16x32_bf16 v[142:145], v[192:195], v[102:105], v[142:145]
	ds_read_b128 v[192:195], v224 offset:22528
	s_waitcnt lgkmcnt(3)
	v_mfma_f32_16x16x32_bf16 v[114:117], v[180:183], v[82:85], v[114:117]
	v_mfma_f32_16x16x32_bf16 v[118:121], v[180:183], v[106:109], v[118:121]
	ds_read_b128 v[180:183], v225 offset:16384
	s_waitcnt lgkmcnt(3)
	v_mfma_f32_16x16x32_bf16 v[122:125], v[184:187], v[82:85], v[122:125]
	v_mfma_f32_16x16x32_bf16 v[126:129], v[184:187], v[106:109], v[126:129]
	ds_read_b128 v[184:187], v225 offset:18432
	s_waitcnt lgkmcnt(3)
	v_mfma_f32_16x16x32_bf16 v[130:133], v[188:191], v[82:85], v[130:133]
	v_mfma_f32_16x16x32_bf16 v[134:137], v[188:191], v[106:109], v[134:137]
	ds_read_b128 v[188:191], v225 offset:20480
	s_waitcnt lgkmcnt(3)
	v_mfma_f32_16x16x32_bf16 v[138:141], v[192:195], v[82:85], v[138:141]
	v_mfma_f32_16x16x32_bf16 v[142:145], v[192:195], v[106:109], v[142:145]
	ds_read_b128 v[192:195], v225 offset:22528
	s_waitcnt lgkmcnt(3)
	v_mfma_f32_16x16x32_bf16 v[114:117], v[180:183], v[86:89], v[114:117]
	v_mfma_f32_16x16x32_bf16 v[118:121], v[180:183], v[110:113], v[118:121]
	s_waitcnt lgkmcnt(2)
	v_mfma_f32_16x16x32_bf16 v[122:125], v[184:187], v[86:89], v[122:125]
	v_mfma_f32_16x16x32_bf16 v[126:129], v[184:187], v[110:113], v[126:129]
	s_waitcnt lgkmcnt(1)
	v_mfma_f32_16x16x32_bf16 v[130:133], v[188:191], v[86:89], v[130:133]
	v_mfma_f32_16x16x32_bf16 v[134:137], v[188:191], v[110:113], v[134:137]
	s_waitcnt lgkmcnt(0)
	v_mfma_f32_16x16x32_bf16 v[138:141], v[192:195], v[86:89], v[138:141]
	v_mfma_f32_16x16x32_bf16 v[142:145], v[192:195], v[110:113], v[142:145]
	s_nop 7
	s_add_u32 s36, s42, 63
	s_cmp_gt_u32 s36, s43
	s_cbranch_scc0 .Lm16_nomask_s0
; __device__ __forceinline__ void mask_tile(f32x16& p0, f32x16& p1, int dq, unsigned W) {
;     const float NEG = -__builtin_inff();
; #pragma unroll
;     for (int r = 0; r < 16; ++r) { const int c = (r & 3) + 8 * (r >> 2);
;         if ((unsigned)(dq - c) >= W) p0[r] = NEG;
;         if ((unsigned)(dq - c - 32) >= W) p1[r] = NEG; }
; }
; template <bool MLA> __device__ __forceinline__ void attn_unit(const AttnP& P, int b, int hh, int qb, LAS char* lds) {
;     ...
;             if (kb + 63 > qlo || (!MLA && kb <= qlo + 31 - W)) mask_tile(p0, p1, dq, (unsigned)W);
	s_sub_u32 s36, s43, s42
	v_add_u32_e32 v244, s36, v243
	v_cmp_gt_i32_e32 vcc, 0, v244
	s_nop 1
	v_cndmask_b32_e32 v114, v114, v245, vcc
	v_cmp_gt_i32_e32 vcc, 1, v244
	s_nop 1
	v_cndmask_b32_e32 v115, v115, v245, vcc
	v_cmp_gt_i32_e32 vcc, 2, v244
	s_nop 1
	v_cndmask_b32_e32 v116, v116, v245, vcc
	v_cmp_gt_i32_e32 vcc, 3, v244
	s_nop 1
	v_cndmask_b32_e32 v117, v117, v245, vcc
	v_cmp_gt_i32_e32 vcc, -16, v244
	s_nop 1
	v_cndmask_b32_e32 v118, v118, v245, vcc
	v_cmp_gt_i32_e32 vcc, -15, v244
	s_nop 1
	v_cndmask_b32_e32 v119, v119, v245, vcc
	v_cmp_gt_i32_e32 vcc, -14, v244
	s_nop 1
	v_cndmask_b32_e32 v120, v120, v245, vcc
	v_cmp_gt_i32_e32 vcc, -13, v244
	s_nop 1
	v_cndmask_b32_e32 v121, v121, v245, vcc
	v_cmp_gt_i32_e32 vcc, 16, v244
	s_nop 1
	v_cndmask_b32_e32 v122, v122, v245, vcc
	v_cmp_gt_i32_e32 vcc, 17, v244
	s_nop 1
	v_cndmask_b32_e32 v123, v123, v245, vcc
	v_cmp_gt_i32_e32 vcc, 18, v244
	s_nop 1
	v_cndmask_b32_e32 v124, v124, v245, vcc
	v_cmp_gt_i32_e32 vcc, 19, v244
	s_nop 1
	v_cndmask_b32_e32 v125, v125, v245, vcc
	v_cmp_gt_i32_e32 vcc, 0, v244
	s_nop 1
	v_cndmask_b32_e32 v126, v126, v245, vcc
	v_cmp_gt_i32_e32 vcc, 1, v244
	s_nop 1
	v_cndmask_b32_e32 v127, v127, v245, vcc
	v_cmp_gt_i32_e32 vcc, 2, v244
	s_nop 1
	v_cndmask_b32_e32 v128, v128, v245, vcc
	v_cmp_gt_i32_e32 vcc, 3, v244
	s_nop 1
	v_cndmask_b32_e32 v129, v129, v245, vcc
	v_cmp_gt_i32_e32 vcc, 32, v244
	s_nop 1
	v_cndmask_b32_e32 v130, v130, v245, vcc
	v_cmp_gt_i32_e32 vcc, 33, v244
	s_nop 1
	v_cndmask_b32_e32 v131, v131, v245, vcc
	v_cmp_gt_i32_e32 vcc, 34, v244
	s_nop 1
	v_cndmask_b32_e32 v132, v132, v245, vcc
	v_cmp_gt_i32_e32 vcc, 35, v244
	s_nop 1
	v_cndmask_b32_e32 v133, v133, v245, vcc
	v_cmp_gt_i32_e32 vcc, 16, v244
	s_nop 1
	v_cndmask_b32_e32 v134, v134, v245, vcc
	v_cmp_gt_i32_e32 vcc, 17, v244
	s_nop 1
	v_cndmask_b32_e32 v135, v135, v245, vcc
	v_cmp_gt_i32_e32 vcc, 18, v244
	s_nop 1
	v_cndmask_b32_e32 v136, v136, v245, vcc
	v_cmp_gt_i32_e32 vcc, 19, v244
	s_nop 1
	v_cndmask_b32_e32 v137, v137, v245, vcc
	v_cmp_gt_i32_e32 vcc, 48, v244
	s_nop 1
	v_cndmask_b32_e32 v138, v138, v245, vcc
	v_cmp_gt_i32_e32 vcc, 49, v244
	s_nop 1
	v_cndmask_b32_e32 v139, v139, v245, vcc
	v_cmp_gt_i32_e32 vcc, 50, v244
	s_nop 1
	v_cndmask_b32_e32 v140, v140, v245, vcc
	v_cmp_gt_i32_e32 vcc, 51, v244
	s_nop 1
	v_cndmask_b32_e32 v141, v141, v245, vcc
	v_cmp_gt_i32_e32 vcc, 32, v244
	s_nop 1
	v_cndmask_b32_e32 v142, v142, v245, vcc
	v_cmp_gt_i32_e32 vcc, 33, v244
	s_nop 1
	v_cndmask_b32_e32 v143, v143, v245, vcc
	v_cmp_gt_i32_e32 vcc, 34, v244
	s_nop 1
	v_cndmask_b32_e32 v144, v144, v245, vcc
	v_cmp_gt_i32_e32 vcc, 35, v244
	s_nop 1
	v_cndmask_b32_e32 v145, v145, v245, vcc
